# v33
# speedup vs baseline: 1.0117x; 1.0022x over previous
.LBB0_275:
	s_lshl_b32 s65, s52, 6
	s_cmp_lt_u32 s52, 31
	s_cselect_b64 s[12:13], -1, 0
	s_cmp_gt_u32 s52, 30
	s_cbranch_scc1 .LBB0_277
	v_add_u32_e32 v68, s65, v133
	v_ashrrev_i32_e32 v69, 31, v68
	v_lshlrev_b64 v[68:69], 11, v[68:69]
	v_lshl_add_u64 v[76:77], v[88:89], 0, v[68:69]
	v_add_co_u32_e32 v80, vcc, 0x1000, v76
	s_nop 0
	v_addc_co_u32_e32 v81, vcc, 0, v77, vcc
	v_lshl_add_u64 v[160:161], v[152:153], 0, s[82:83]
	v_lshl_add_u64 v[162:163], v[154:155], 0, s[82:83]
	v_lshl_add_u64 v[164:165], v[156:157], 0, s[82:83]
	v_lshl_add_u64 v[166:167], v[158:159], 0, s[82:83]
	global_load_ushort v141, v[160:161], off
	global_load_ushort v142, v[160:161], off offset:2048
	global_load_ushort v143, v[162:163], off
	global_load_ushort v144, v[162:163], off offset:2048
	global_load_ushort v145, v[164:165], off
	global_load_ushort v146, v[164:165], off offset:2048
	global_load_ushort v147, v[166:167], off
	global_load_ushort v148, v[166:167], off offset:2048

.LBB0_285:
	s_or_b64 exec, exec, s[16:17]
	s_cmp_gt_u32 s52, 30
	s_cbranch_scc1 .Lrnn_nox
	global_load_dwordx4 v[52:55], v[76:77], off
	global_load_dwordx4 v[56:59], v[76:77], off offset:2048
	global_load_dwordx4 v[60:63], v[80:81], off
	global_load_dwordx4 v[64:67], v[80:81], off offset:2048
.Lrnn_nox:
	v_pk_fma_f32 v[94:95], v[24:25], v[94:95], v[16:17]
	v_pk_fma_f32 v[96:97], v[26:27], v[96:97], v[18:19]
	v_pk_fma_f32 v[98:99], v[20:21], v[98:99], v[12:13]
	v_pk_fma_f32 v[100:101], v[22:23], v[100:101], v[14:15]
	v_pk_fma_f32 v[92:93], v[28:29], v[92:93], v[94:95]
	v_pk_fma_f32 v[94:95], v[30:31], v[102:103], v[96:97]
	v_pk_fma_f32 v[96:97], v[32:33], v[104:105], v[98:99]
	v_pk_fma_f32 v[98:99], v[34:35], v[106:107], v[100:101]
	v_pk_fma_f32 v[92:93], v[36:37], v[110:111], v[92:93]
	v_pk_fma_f32 v[94:95], v[38:39], v[112:113], v[94:95]
	v_pk_fma_f32 v[100:101], v[40:41], v[114:115], v[96:97]
	v_pk_fma_f32 v[102:103], v[42:43], v[116:117], v[98:99]
	v_pk_fma_f32 v[92:93], v[44:45], v[108:109], v[92:93]
	v_pk_fma_f32 v[94:95], v[46:47], v[122:123], v[94:95]
	v_cvt_pk_bf16_f32 v96, v92, v93
	v_pk_fma_f32 v[100:101], v[48:49], v[120:121], v[100:101]
	v_cvt_pk_bf16_f32 v97, v94, v95
	v_pk_fma_f32 v[102:103], v[50:51], v[118:119], v[102:103]
	v_cvt_pk_bf16_f32 v98, v100, v101
	s_nop 0
	v_cvt_pk_bf16_f32 v99, v102, v103
	ds_write_b128 v137, v[96:99]
	ds_write_b128 v138, v[92:95] offset:9216
	ds_write_b128 v138, v[100:103] offset:9232
	s_waitcnt lgkmcnt(0)
	s_barrier
	ds_read_b128 v[92:95], v139
	ds_read_b128 v[96:99], v139 offset:64
	s_waitcnt lgkmcnt(1)
	v_mfma_f32_16x16x32_bf16 v[92:95], v[92:95], v[4:7], 0
	s_waitcnt lgkmcnt(0)
	v_mfma_f32_16x16x32_bf16 v[92:95], v[96:99], v[8:11], v[92:95]
	s_nop 7
	v_add_f32_e32 v92, v124, v92
	v_mul_f32_e32 v92, 0xbfb8aa3b, v92
	v_exp_f32_e32 v92, v92
	v_add_f32_e32 v93, v124, v93
	v_mul_f32_e32 v93, 0xbfb8aa3b, v93
	v_exp_f32_e32 v93, v93
	v_add_f32_e32 v92, 1.0, v92
	v_div_scale_f32 v96, s[16:17], v92, v92, 1.0
	v_rcp_f32_e32 v97, v96
	v_add_f32_e32 v93, 1.0, v93
	v_add_f32_e32 v94, v124, v94
	v_mul_f32_e32 v94, 0xbfb8aa3b, v94
	v_fma_f32 v98, -v96, v97, 1.0
	v_fmac_f32_e32 v97, v98, v97
	v_div_scale_f32 v98, vcc, 1.0, v92, 1.0
	v_mul_f32_e32 v99, v98, v97
	v_fma_f32 v100, -v96, v99, v98
	v_fmac_f32_e32 v99, v100, v97
	v_fma_f32 v96, -v96, v99, v98
	v_div_fmas_f32 v96, v96, v97, v99
	v_div_scale_f32 v97, s[16:17], v93, v93, 1.0
	v_rcp_f32_e32 v98, v97
	v_div_fixup_f32 v92, v96, v92, 1.0
	v_mul_f32_e32 v96, v1, v92
	v_cndmask_b32_e64 v92, v92, v96, s[6:7]
	v_fma_f32 v96, -v97, v98, 1.0
	v_fmac_f32_e32 v98, v96, v98
	v_div_scale_f32 v96, vcc, 1.0, v93, 1.0
	v_mul_f32_e32 v99, v96, v98
	v_exp_f32_e32 v94, v94
	v_fma_f32 v100, -v97, v99, v96
	v_fmac_f32_e32 v99, v100, v98
	v_fma_f32 v96, -v97, v99, v96
	v_div_fmas_f32 v96, v96, v98, v99
	v_add_f32_e32 v94, 1.0, v94
	v_div_fixup_f32 v93, v96, v93, 1.0
	v_div_scale_f32 v96, s[16:17], v94, v94, 1.0
	v_rcp_f32_e32 v97, v96
	v_mul_f32_e32 v98, v1, v93
	v_cndmask_b32_e64 v93, v93, v98, s[6:7]
	ds_write2st64_b32 v140, v92, v93 offset1:1
	v_fma_f32 v92, -v96, v97, 1.0
	v_add_f32_e32 v95, v124, v95
	v_fmac_f32_e32 v97, v92, v97
	v_div_scale_f32 v92, vcc, 1.0, v94, 1.0
	v_mul_f32_e32 v95, 0xbfb8aa3b, v95
	v_mul_f32_e32 v93, v92, v97
	v_exp_f32_e32 v95, v95
	v_fma_f32 v98, -v96, v93, v92
	v_fmac_f32_e32 v93, v98, v97
	v_fma_f32 v92, -v96, v93, v92
	v_div_fmas_f32 v92, v92, v97, v93
	v_add_f32_e32 v93, 1.0, v95
	v_div_scale_f32 v95, s[16:17], v93, v93, 1.0
	v_rcp_f32_e32 v96, v95
	v_div_fixup_f32 v92, v92, v94, 1.0
	v_mul_f32_e32 v94, v1, v92
	v_cndmask_b32_e64 v92, v92, v94, s[6:7]
	v_fma_f32 v94, -v95, v96, 1.0
	v_fmac_f32_e32 v96, v94, v96
	v_div_scale_f32 v94, vcc, 1.0, v93, 1.0
	v_mul_f32_e32 v97, v94, v96
	v_fma_f32 v98, -v95, v97, v94
	v_fmac_f32_e32 v97, v98, v96
	v_fma_f32 v94, -v95, v97, v94
	v_div_fmas_f32 v94, v94, v96, v97
	v_div_fixup_f32 v93, v94, v93, 1.0
	v_mul_f32_e32 v94, v1, v93
	v_cndmask_b32_e64 v93, v93, v94, s[6:7]
	ds_write2st64_b32 v140, v92, v93 offset0:2 offset1:3
	ds_read_b128 v[92:95], v139 offset:2304
	ds_read_b128 v[96:99], v139 offset:2368
	s_waitcnt lgkmcnt(1)
	v_mfma_f32_16x16x32_bf16 v[92:95], v[92:95], v[4:7], 0
	s_waitcnt lgkmcnt(0)
	v_mfma_f32_16x16x32_bf16 v[92:95], v[96:99], v[8:11], v[92:95]
	s_nop 7
	v_add_f32_e32 v92, v124, v92
	v_mul_f32_e32 v92, 0xbfb8aa3b, v92
	v_exp_f32_e32 v92, v92
	v_add_f32_e32 v93, v124, v93
	v_mul_f32_e32 v93, 0xbfb8aa3b, v93
	v_exp_f32_e32 v93, v93
	v_add_f32_e32 v92, 1.0, v92
	v_div_scale_f32 v96, s[16:17], v92, v92, 1.0
	v_rcp_f32_e32 v97, v96
	v_add_f32_e32 v93, 1.0, v93
	v_add_f32_e32 v94, v124, v94
	v_mul_f32_e32 v94, 0xbfb8aa3b, v94
	v_fma_f32 v98, -v96, v97, 1.0
	v_fmac_f32_e32 v97, v98, v97
	v_div_scale_f32 v98, vcc, 1.0, v92, 1.0
	v_mul_f32_e32 v99, v98, v97
	v_fma_f32 v100, -v96, v99, v98
	v_fmac_f32_e32 v99, v100, v97
	v_fma_f32 v96, -v96, v99, v98
	v_div_fmas_f32 v96, v96, v97, v99
	v_div_scale_f32 v97, s[16:17], v93, v93, 1.0
	v_rcp_f32_e32 v98, v97
	v_div_fixup_f32 v92, v96, v92, 1.0
	v_mul_f32_e32 v96, v1, v92
	v_cndmask_b32_e64 v92, v92, v96, s[6:7]
	v_fma_f32 v96, -v97, v98, 1.0
	v_fmac_f32_e32 v98, v96, v98
	v_div_scale_f32 v96, vcc, 1.0, v93, 1.0
	v_mul_f32_e32 v99, v96, v98
	v_exp_f32_e32 v94, v94
	v_fma_f32 v100, -v97, v99, v96
	v_fmac_f32_e32 v99, v100, v98
	v_fma_f32 v96, -v97, v99, v96
	v_div_fmas_f32 v96, v96, v98, v99
	v_add_f32_e32 v94, 1.0, v94
	v_div_fixup_f32 v93, v96, v93, 1.0
	v_div_scale_f32 v96, s[16:17], v94, v94, 1.0
	v_rcp_f32_e32 v97, v96
	v_mul_f32_e32 v98, v1, v93
	v_cndmask_b32_e64 v93, v93, v98, s[6:7]
	ds_write2st64_b32 v140, v92, v93 offset0:16 offset1:17
	v_fma_f32 v92, -v96, v97, 1.0
	v_add_f32_e32 v95, v124, v95
	v_fmac_f32_e32 v97, v92, v97
	v_div_scale_f32 v92, vcc, 1.0, v94, 1.0
	v_mul_f32_e32 v95, 0xbfb8aa3b, v95
	v_mul_f32_e32 v93, v92, v97
	v_exp_f32_e32 v95, v95
	v_fma_f32 v98, -v96, v93, v92
	v_fmac_f32_e32 v93, v98, v97
	v_fma_f32 v92, -v96, v93, v92
	v_div_fmas_f32 v92, v92, v97, v93
	v_add_f32_e32 v93, 1.0, v95
	v_div_scale_f32 v95, s[16:17], v93, v93, 1.0
	v_rcp_f32_e32 v96, v95
	v_div_fixup_f32 v92, v92, v94, 1.0
	v_mul_f32_e32 v94, v1, v92
	v_cndmask_b32_e64 v92, v92, v94, s[6:7]
	v_fma_f32 v94, -v95, v96, 1.0
	v_fmac_f32_e32 v96, v94, v96
	v_div_scale_f32 v94, vcc, 1.0, v93, 1.0
	v_mul_f32_e32 v97, v94, v96
	v_fma_f32 v98, -v95, v97, v94
	v_fmac_f32_e32 v97, v98, v96
	v_fma_f32 v94, -v95, v97, v94
	v_div_fmas_f32 v94, v94, v96, v97
	v_div_fixup_f32 v93, v94, v93, 1.0
	v_mul_f32_e32 v94, v1, v93
	v_cndmask_b32_e64 v93, v93, v94, s[6:7]
	ds_write2st64_b32 v140, v92, v93 offset0:18 offset1:19
	ds_read_b128 v[92:95], v139 offset:4608
	ds_read_b128 v[96:99], v139 offset:4672
	s_waitcnt lgkmcnt(1)
	v_mfma_f32_16x16x32_bf16 v[92:95], v[92:95], v[4:7], 0
	s_waitcnt lgkmcnt(0)
	v_mfma_f32_16x16x32_bf16 v[92:95], v[96:99], v[8:11], v[92:95]
	s_nop 7
	v_add_f32_e32 v92, v124, v92
	v_mul_f32_e32 v92, 0xbfb8aa3b, v92
	v_exp_f32_e32 v92, v92
	v_add_f32_e32 v93, v124, v93
	v_mul_f32_e32 v93, 0xbfb8aa3b, v93
	v_exp_f32_e32 v93, v93
	v_add_f32_e32 v92, 1.0, v92
	v_div_scale_f32 v96, s[16:17], v92, v92, 1.0
	v_rcp_f32_e32 v97, v96
	v_add_f32_e32 v93, 1.0, v93
	v_add_f32_e32 v94, v124, v94
	v_mul_f32_e32 v94, 0xbfb8aa3b, v94
	v_fma_f32 v98, -v96, v97, 1.0
	v_fmac_f32_e32 v97, v98, v97
	v_div_scale_f32 v98, vcc, 1.0, v92, 1.0
	v_mul_f32_e32 v99, v98, v97
	v_fma_f32 v100, -v96, v99, v98
	v_fmac_f32_e32 v99, v100, v97
	v_fma_f32 v96, -v96, v99, v98
	v_div_fmas_f32 v96, v96, v97, v99
	v_div_scale_f32 v97, s[16:17], v93, v93, 1.0
	v_rcp_f32_e32 v98, v97
	v_div_fixup_f32 v92, v96, v92, 1.0
	v_mul_f32_e32 v96, v1, v92
	v_cndmask_b32_e64 v92, v92, v96, s[6:7]
	v_fma_f32 v96, -v97, v98, 1.0
	v_fmac_f32_e32 v98, v96, v98
	v_div_scale_f32 v96, vcc, 1.0, v93, 1.0
	v_mul_f32_e32 v99, v96, v98
	v_exp_f32_e32 v94, v94
	v_fma_f32 v100, -v97, v99, v96
	v_fmac_f32_e32 v99, v100, v98
	v_fma_f32 v96, -v97, v99, v96
	v_div_fmas_f32 v96, v96, v98, v99
	v_add_f32_e32 v94, 1.0, v94
	v_div_fixup_f32 v93, v96, v93, 1.0
	v_div_scale_f32 v96, s[16:17], v94, v94, 1.0
	v_rcp_f32_e32 v97, v96
	v_mul_f32_e32 v98, v1, v93
	v_cndmask_b32_e64 v93, v93, v98, s[6:7]
	ds_write2st64_b32 v140, v92, v93 offset0:32 offset1:33
	v_fma_f32 v92, -v96, v97, 1.0
	v_add_f32_e32 v95, v124, v95
	v_fmac_f32_e32 v97, v92, v97
	v_div_scale_f32 v92, vcc, 1.0, v94, 1.0
	v_mul_f32_e32 v95, 0xbfb8aa3b, v95
	v_mul_f32_e32 v93, v92, v97
	v_exp_f32_e32 v95, v95
	v_fma_f32 v98, -v96, v93, v92
	v_fmac_f32_e32 v93, v98, v97
	v_fma_f32 v92, -v96, v93, v92
	v_div_fmas_f32 v92, v92, v97, v93
	v_add_f32_e32 v93, 1.0, v95
	v_div_scale_f32 v95, s[16:17], v93, v93, 1.0
	v_rcp_f32_e32 v96, v95
	v_div_fixup_f32 v92, v92, v94, 1.0
	v_mul_f32_e32 v94, v1, v92
	v_cndmask_b32_e64 v92, v92, v94, s[6:7]
	v_fma_f32 v94, -v95, v96, 1.0
	v_fmac_f32_e32 v96, v94, v96
	v_div_scale_f32 v94, vcc, 1.0, v93, 1.0
	v_mul_f32_e32 v97, v94, v96
	v_fma_f32 v98, -v95, v97, v94
	v_fmac_f32_e32 v97, v98, v96
	v_fma_f32 v94, -v95, v97, v94
	v_div_fmas_f32 v94, v94, v96, v97
	v_div_fixup_f32 v93, v94, v93, 1.0
	v_mul_f32_e32 v94, v1, v93
	v_cndmask_b32_e64 v93, v93, v94, s[6:7]
	ds_write2st64_b32 v140, v92, v93 offset0:34 offset1:35
	ds_read_b128 v[92:95], v139 offset:6912
	ds_read_b128 v[96:99], v139 offset:6976
	s_waitcnt lgkmcnt(1)
	v_mfma_f32_16x16x32_bf16 v[92:95], v[92:95], v[4:7], 0
	s_waitcnt lgkmcnt(0)
	v_mfma_f32_16x16x32_bf16 v[92:95], v[96:99], v[8:11], v[92:95]
	s_nop 7
	v_add_f32_e32 v92, v124, v92
	v_mul_f32_e32 v92, 0xbfb8aa3b, v92
	v_exp_f32_e32 v92, v92
	v_add_f32_e32 v93, v124, v93
	v_mul_f32_e32 v93, 0xbfb8aa3b, v93
	v_exp_f32_e32 v93, v93
	v_add_f32_e32 v92, 1.0, v92
	v_div_scale_f32 v96, s[16:17], v92, v92, 1.0
	v_rcp_f32_e32 v97, v96
	v_add_f32_e32 v93, 1.0, v93
	v_add_f32_e32 v94, v124, v94
	v_mul_f32_e32 v94, 0xbfb8aa3b, v94
	v_fma_f32 v98, -v96, v97, 1.0
	v_fmac_f32_e32 v97, v98, v97
	v_div_scale_f32 v98, vcc, 1.0, v92, 1.0
	v_mul_f32_e32 v99, v98, v97
	v_fma_f32 v100, -v96, v99, v98
	v_fmac_f32_e32 v99, v100, v97
	v_fma_f32 v96, -v96, v99, v98
	v_div_fmas_f32 v96, v96, v97, v99
	v_div_scale_f32 v97, s[16:17], v93, v93, 1.0
	v_rcp_f32_e32 v98, v97
	v_div_fixup_f32 v92, v96, v92, 1.0
	v_mul_f32_e32 v96, v1, v92
	v_cndmask_b32_e64 v92, v92, v96, s[6:7]
	v_fma_f32 v96, -v97, v98, 1.0
	v_fmac_f32_e32 v98, v96, v98
	v_div_scale_f32 v96, vcc, 1.0, v93, 1.0
	v_mul_f32_e32 v99, v96, v98
	v_exp_f32_e32 v94, v94
	v_fma_f32 v100, -v97, v99, v96
	v_fmac_f32_e32 v99, v100, v98
	v_fma_f32 v96, -v97, v99, v96
	v_div_fmas_f32 v96, v96, v98, v99
	v_add_f32_e32 v94, 1.0, v94
	v_div_fixup_f32 v93, v96, v93, 1.0
	v_div_scale_f32 v96, s[16:17], v94, v94, 1.0
	v_rcp_f32_e32 v97, v96
	v_mul_f32_e32 v98, v1, v93
	v_cndmask_b32_e64 v93, v93, v98, s[6:7]
	ds_write2st64_b32 v140, v92, v93 offset0:48 offset1:49
	v_fma_f32 v92, -v96, v97, 1.0
	v_add_f32_e32 v95, v124, v95
	v_fmac_f32_e32 v97, v92, v97
	v_div_scale_f32 v92, vcc, 1.0, v94, 1.0
	v_mul_f32_e32 v95, 0xbfb8aa3b, v95
	v_mul_f32_e32 v93, v92, v97
	v_exp_f32_e32 v95, v95
	v_fma_f32 v98, -v96, v93, v92
	v_fmac_f32_e32 v93, v98, v97
	v_fma_f32 v92, -v96, v93, v92
	v_div_fmas_f32 v92, v92, v97, v93
	v_add_f32_e32 v93, 1.0, v95
	v_div_scale_f32 v95, s[16:17], v93, v93, 1.0
	v_rcp_f32_e32 v96, v95
	v_div_fixup_f32 v92, v92, v94, 1.0
	v_mul_f32_e32 v94, v1, v92
	v_cndmask_b32_e64 v92, v92, v94, s[6:7]
	v_fma_f32 v94, -v95, v96, 1.0
	v_fmac_f32_e32 v96, v94, v96
	v_div_scale_f32 v94, vcc, 1.0, v93, 1.0
	v_mul_f32_e32 v97, v94, v96
	v_fma_f32 v98, -v95, v97, v94
	v_fmac_f32_e32 v97, v98, v96
	v_fma_f32 v94, -v95, v97, v94
	v_div_fmas_f32 v94, v94, v96, v97
	v_div_fixup_f32 v93, v94, v93, 1.0
	v_mul_f32_e32 v94, v1, v93
	v_cndmask_b32_e64 v93, v93, v94, s[6:7]
	ds_write2st64_b32 v140, v92, v93 offset0:50 offset1:51
	s_waitcnt lgkmcnt(0)
	s_barrier
	ds_read2st64_b32 v[94:95], v135 offset0:100 offset1:101
	ds_read2st64_b32 v[96:97], v135 offset0:102 offset1:103
	ds_read2st64_b32 v[104:105], v135 offset0:104 offset1:105
	ds_read2st64_b32 v[106:107], v135 offset0:106 offset1:107
	s_and_b32 s16, s65, 64
	s_waitcnt lgkmcnt(3)
	v_add_f32_e32 v93, v94, v94
	v_mul_f32_e32 v92, 0x3fb8aa3b, v94
	v_fmamk_f32 v94, v93, 0x39500d01, v210
	v_fmaak_f32 v94, v93, v94, 0x3c088889
	v_exp_f32_e32 v92, v92
	v_fmaak_f32 v94, v93, v94, 0x3d2aaaab
	v_fmaak_f32 v94, v93, v94, 0x3e2aaaab
	v_fma_f32 v94, v93, v94, 0.5
	v_fma_f32 v94, v93, v94, 1.0
	v_mul_f32_e64 v94, v94, -v93
	v_fma_f32 v98, -v92, v92, 1.0
	v_cmp_lt_f32_e32 vcc, s29, v93
	s_nop 1
	v_cndmask_b32_e32 v93, v98, v94, vcc
	ds_read2st64_b32 v[98:99], v135 offset0:36 offset1:37
	ds_read2st64_b32 v[100:101], v135 offset0:164 offset1:165
	ds_read2st64_b32 v[102:103], v135 offset0:166 offset1:167
	ds_read2st64_b32 v[108:109], v135 offset0:168 offset1:169
	ds_read2st64_b32 v[110:111], v135 offset0:170 offset1:171
	ds_read2st64_b32 v[112:113], v135 offset0:38 offset1:39
	ds_read2st64_b32 v[114:115], v135 offset0:40 offset1:41
	ds_read2st64_b32 v[116:117], v135 offset0:42 offset1:43
	s_waitcnt lgkmcnt(6)
	v_mul_f32_e32 v94, v100, v98
	v_mul_f32_e32 v98, 0x3fb8aa3b, v95
	v_add_f32_e32 v95, v95, v95
	v_fmamk_f32 v100, v95, 0x39500d01, v210
	v_fmaak_f32 v100, v95, v100, 0x3c088889
	v_exp_f32_e32 v98, v98
	v_fmaak_f32 v100, v95, v100, 0x3d2aaaab
	v_fmaak_f32 v100, v95, v100, 0x3e2aaaab
	v_sqrt_f32_e32 v93, v93
	v_fma_f32 v100, v95, v100, 0.5
	v_fma_f32 v100, v95, v100, 1.0
	v_mul_f32_e64 v100, v100, -v95
	v_fma_f32 v118, -v98, v98, 1.0
	v_cmp_lt_f32_e32 vcc, s29, v95
	s_nop 1
	v_cndmask_b32_e32 v95, v118, v100, vcc
	v_sqrt_f32_e32 v100, v95
	v_mul_f32_e32 v95, v94, v93
	v_mul_f32_e32 v94, 0x3fb8aa3b, v96
	v_mul_f32_e32 v93, v101, v99
	v_exp_f32_e32 v99, v94
	v_add_f32_e32 v94, v96, v96
	v_fmamk_f32 v96, v94, 0x39500d01, v210
	v_fmaak_f32 v96, v94, v96, 0x3c088889
	v_fmaak_f32 v96, v94, v96, 0x3d2aaaab
	v_fmaak_f32 v96, v94, v96, 0x3e2aaaab
	v_fma_f32 v96, v94, v96, 0.5
	v_fma_f32 v96, v94, v96, 1.0
	v_mul_f32_e32 v93, v93, v100
	v_mul_f32_e64 v96, v96, -v94
	v_fma_f32 v100, -v99, v99, 1.0
	v_cmp_lt_f32_e32 vcc, s29, v94
	v_fmac_f32_e32 v95, 0, v92
	v_fmac_f32_e32 v93, v98, v95
	v_cndmask_b32_e32 v94, v100, v96, vcc
	v_sqrt_f32_e32 v94, v94
	s_waitcnt lgkmcnt(2)
	v_mul_f32_e32 v96, v102, v112
	v_mul_f32_e32 v98, v92, v98
	v_mul_f32_e32 v94, v96, v94
	v_mul_f32_e32 v96, 0x3fb8aa3b, v97
	v_exp_f32_e32 v100, v96
	v_add_f32_e32 v96, v97, v97
	v_fmamk_f32 v97, v96, 0x39500d01, v210
	v_fmaak_f32 v97, v96, v97, 0x3c088889
	v_fmaak_f32 v97, v96, v97, 0x3d2aaaab
	v_fmaak_f32 v97, v96, v97, 0x3e2aaaab
	v_fma_f32 v97, v96, v97, 0.5
	v_fma_f32 v97, v96, v97, 1.0
	v_mul_f32_e64 v97, v97, -v96
	v_fma_f32 v101, -v100, v100, 1.0
	v_cmp_lt_f32_e32 vcc, s29, v96
	v_fmac_f32_e32 v94, v99, v93
	s_nop 0
	v_cndmask_b32_e32 v96, v101, v97, vcc
	v_sqrt_f32_e32 v96, v96
	v_mul_f32_e32 v97, v103, v113
	v_mul_f32_e32 v101, v98, v99
	v_mul_f32_e32 v96, v97, v96
	v_mul_f32_e32 v97, 0x3fb8aa3b, v104
	v_exp_f32_e32 v99, v97
	v_add_f32_e32 v97, v104, v104
	v_fmamk_f32 v102, v97, 0x39500d01, v210
	v_fmaak_f32 v102, v97, v102, 0x3c088889
	v_fmaak_f32 v102, v97, v102, 0x3d2aaaab
	v_fmaak_f32 v102, v97, v102, 0x3e2aaaab
	v_fma_f32 v102, v97, v102, 0.5
	v_fma_f32 v102, v97, v102, 1.0
	v_mul_f32_e64 v102, v102, -v97
	v_fma_f32 v103, -v99, v99, 1.0
	v_cmp_lt_f32_e32 vcc, s29, v97
	v_fmac_f32_e32 v96, v100, v94
	s_nop 0
	v_cndmask_b32_e32 v97, v103, v102, vcc
	v_sqrt_f32_e32 v97, v97
	v_add_f32_e32 v102, v105, v105
	v_mul_f32_e32 v103, v101, v100
	s_waitcnt lgkmcnt(1)
	v_mul_f32_e32 v100, v108, v114
	v_fmamk_f32 v104, v102, 0x39500d01, v210
	v_mul_f32_e32 v97, v100, v97
	v_mul_f32_e32 v100, 0x3fb8aa3b, v105
	v_fmaak_f32 v104, v102, v104, 0x3c088889
	v_exp_f32_e32 v100, v100
	v_fmaak_f32 v104, v102, v104, 0x3d2aaaab
	v_fmaak_f32 v104, v102, v104, 0x3e2aaaab
	v_fma_f32 v104, v102, v104, 0.5
	v_fma_f32 v104, v102, v104, 1.0
	v_mul_f32_e64 v104, v104, -v102
	v_fma_f32 v105, -v100, v100, 1.0
	v_cmp_lt_f32_e32 vcc, s29, v102
	v_fmac_f32_e32 v97, v99, v96
	s_nop 0
	v_cndmask_b32_e32 v102, v105, v104, vcc
	v_sqrt_f32_e32 v102, v102
	v_mul_f32_e32 v104, v103, v99
	v_mul_f32_e32 v99, v109, v115
	v_mul_f32_e32 v99, v99, v102
	v_mul_f32_e32 v102, 0x3fb8aa3b, v106
	v_exp_f32_e32 v108, v102
	v_add_f32_e32 v102, v106, v106
	v_fmamk_f32 v105, v102, 0x39500d01, v210
	v_fmaak_f32 v105, v102, v105, 0x3c088889
	v_fmaak_f32 v105, v102, v105, 0x3d2aaaab
	v_fmaak_f32 v105, v102, v105, 0x3e2aaaab
	v_fma_f32 v105, v102, v105, 0.5
	v_fma_f32 v105, v102, v105, 1.0
	v_mul_f32_e64 v105, v105, -v102
	v_fma_f32 v106, -v108, v108, 1.0
	v_cmp_lt_f32_e32 vcc, s29, v102
	v_fmac_f32_e32 v99, v100, v97
	s_nop 0
	v_cndmask_b32_e32 v102, v106, v105, vcc
	v_sqrt_f32_e32 v102, v102
	v_mul_f32_e32 v105, v104, v100
	s_waitcnt lgkmcnt(0)
	v_mul_f32_e32 v100, v110, v116
	v_mul_f32_e32 v102, v100, v102
	v_mul_f32_e32 v100, 0x3fb8aa3b, v107
	v_exp_f32_e32 v106, v100
	v_add_f32_e32 v100, v107, v107
	v_fmamk_f32 v107, v100, 0x39500d01, v210
	v_fmaak_f32 v107, v100, v107, 0x3c088889
	v_fmaak_f32 v107, v100, v107, 0x3d2aaaab
	v_fmaak_f32 v107, v100, v107, 0x3e2aaaab
	v_fma_f32 v107, v100, v107, 0.5
	v_fma_f32 v107, v100, v107, 1.0
	v_mul_f32_e64 v107, v107, -v100
	v_fma_f32 v109, -v106, v106, 1.0
	v_cmp_lt_f32_e32 vcc, s29, v100
	v_fmac_f32_e32 v102, v108, v99
	s_nop 0
	v_cndmask_b32_e32 v100, v109, v107, vcc
	v_sqrt_f32_e32 v100, v100
	v_mul_f32_e32 v107, v105, v108
	v_mul_f32_e32 v108, v111, v117
	v_mul_f32_e32 v100, v108, v100
	v_fmac_f32_e32 v100, v106, v102
	v_mul_f32_e32 v106, v107, v106
	v_lshl_add_u32 v108, s16, 2, v132
	ds_write2st64_b32 v125, v106, v100 offset0:228 offset1:236
	s_waitcnt lgkmcnt(0)
	s_barrier
	ds_read_b32 v108, v108 offset:62464
	s_and_saveexec_b64 s[16:17], s[8:9]
	s_cbranch_execz .LBB0_289
	s_mov_b64 s[78:79], 0
	v_mov_b32_e32 v109, v136
	v_mov_b32_e32 v110, v85

.LBB0_292:
	v_mov_b32_e32 v3, v141
	v_mov_b32_e32 v87, v142
	v_mov_b32_e32 v126, v143
	v_mov_b32_e32 v127, v144
	v_mov_b32_e32 v128, v145
	v_mov_b32_e32 v129, v146
	v_mov_b32_e32 v130, v147
	v_mov_b32_e32 v131, v148
	s_branch .LBB0_274
